# v11 + select radix-descent loop specialised by chunk index: counts only the 16/32/48 key registers that can hold real keys, constant keys added arithmetically
# speedup vs baseline: 1.0086x; 1.0086x over previous
; __device__ __forceinline__ void select_item(const Frame& F, int l, int samp, int b, int c, int qg) {
;     int tid = F.tid, lane = F.lane; const int wave = F.wave; asm volatile("" : "+v"(tid), "+v"(lane));
;     __attribute__((address_space(1))) unsigned char* wsl_ = (__attribute__((address_space(1))) unsigned char*)F.ws; asm volatile("" : "+s"(wsl_)); unsigned char* ws = (unsigned char*)wsl_;
;     const int r0 = samp ? MP + b * 64 : b * SEQ + c * 64;
;     const int L = samp ? SKS : 64 * (c + 1);
;     const int nj = L >> 6;
;     u64* SEL = (u64*)(ws + WS_SEL) + (size_t)r0 * 64;
;     const int qA = qg * 16 + wave * 2, qB = qA + 1;
;     u64 mywA = 0ull, mywB = 0ull;
;     if (L <= 256) { mywA = (lane < nj) ? ~0ull : 0ull; mywB = mywA; }
;     else {
;         {
;             unsigned* cw = F.ctl + CW_SCD + 16 * (l * 160 + sel_uid(samp, b, c)); const unsigned need = (unsigned)sel_nchunks(samp, c);
.LBB0_1298:
	s_and_b64 vcc, exec, s[0:1]
	s_cbranch_vccz .LBB0_1458
	s_bfe_u32 s9, s33, 0x60002
	s_ashr_i32 s4, s33, 8
	s_xor_b32 s6, s9, 63
	s_lshr_b32 s98, s6, 4
	s_lshl_b32 s0, s4, 12
	s_lshl_b32 s1, s6, 6
	s_or_b32 s14, s1, s0
	s_lshl_b32 s0, s74, 4
	v_mov_b32_e32 v0, v198
	s_add_i32 s12, s0, s86
	v_mov_b32_e32 v1, v199
	s_mov_b64 s[10:11], s[90:91]
	s_cmp_gt_u32 s6, 3
	s_mov_b64 s[0:1], -1
	s_cbranch_scc0 .LBB0_1455
	s_lshl_b32 s0, s4, 6
	v_readlane_b32 s1, v254, 38
	s_add_i32 s0, s0, s1
	s_add_i32 s0, s0, s6
	s_lshl_b32 s0, s0, 4
	s_ashr_i32 s1, s0, 31
	s_lshl_b64 s[0:1], s[0:1], 2
	v_readlane_b32 s4, v254, 31
	s_add_u32 s0, s4, s0
	v_readlane_b32 s4, v254, 37
	s_addc_u32 s1, s4, s1
	s_sub_i32 s4, 0x47, s9
	s_lshr_b32 s7, s4, 3
	s_mov_b32 s8, 0x400001
	s_branch .LBB0_1302

; __device__ __forceinline__ unsigned ord_key(unsigned u) { return (u & 0x80000000u) ? ~u : (u | 0x80000000u); }
; __device__ __forceinline__ void select_item(const Frame& F, int l, int samp, int b, int c, int qg) {
;     ...
;         for (int j = 0; j < 64; ++j) { keyA[j] = (j < nj) ? ord_key(keyA[j]) : 0x007FFFFFu; keyB[j] = (j < nj) ? ord_key(keyB[j]) : 0x007FFFFFu; }
;         unsigned prefixA = 0u, prefixB = 0u; bool doneA = false, doneB = false;
;     ...
;             const unsigned candA = prefixA | (1u << bit), candB = prefixB | (1u << bit), cA1 = candA - 1u, cB1 = candB - 1u; unsigned a4[4] = {0u, 0u, 0u, 0u}, b4[4] = {0u, 0u, 0u, 0u};
; #pragma unroll
;             for (int j = 0; j < 64; ++j) { a4[j & 3] += min(__builtin_elementwise_sub_sat(keyA[j], cA1), 1u); b4[j & 3] += min(__builtin_elementwise_sub_sat(keyB[j], cB1), 1u); }
;             const int cntA = wave_sum_i_dpp((int)((a4[0] + a4[1]) + (a4[2] + a4[3]))), cntB = wave_sum_i_dpp((int)((b4[0] + b4[1]) + (b4[2] + b4[3])));
;             if (!doneA) { if (cntA >= 256) prefixA = candA; if (cntA == 256) doneA = true; }
;             if (!doneB) { if (cntB >= 256) prefixB = candB; if (cntB == 256) doneB = true; }
;         }
.LBB0_1426:
	s_waitcnt vmcnt(0)
	v_not_b32_e32 v2, v131
	v_cmp_gt_i32_e32 vcc, 0, v131
	s_mov_b32 s10, 0
	s_mov_b32 s11, 31
	v_cndmask_b32_e64 v131, -|v131|, v2, vcc
	v_not_b32_e32 v2, v85
	v_cmp_gt_i32_e32 vcc, 0, v85
	s_mov_b64 s[0:1], 0
	s_mov_b32 s33, 0
	v_cndmask_b32_e64 v85, -|v85|, v2, vcc
	v_not_b32_e32 v2, v84
	v_cmp_gt_i32_e32 vcc, 0, v84
	s_mov_b64 s[42:43], 0
	s_nop 0
	v_cndmask_b32_e64 v130, -|v84|, v2, vcc
	v_not_b32_e32 v2, v129
	v_cmp_gt_i32_e32 vcc, 0, v129
	s_nop 1
	v_cndmask_b32_e64 v84, -|v129|, v2, vcc
	v_not_b32_e32 v2, v83
	v_cmp_gt_i32_e32 vcc, 0, v83
	s_nop 1
	v_cndmask_b32_e64 v129, -|v83|, v2, vcc
	v_not_b32_e32 v2, v128
	v_cmp_gt_i32_e32 vcc, 0, v128
	s_nop 1
	v_cndmask_b32_e64 v83, -|v128|, v2, vcc
	v_not_b32_e32 v2, v82
	v_cmp_gt_i32_e32 vcc, 0, v82
	s_nop 1
	v_cndmask_b32_e64 v128, -|v82|, v2, vcc
	v_not_b32_e32 v2, v127
	v_cmp_gt_i32_e32 vcc, 0, v127
	s_nop 1
	v_cndmask_b32_e64 v82, -|v127|, v2, vcc
	v_not_b32_e32 v2, v81
	v_cmp_gt_i32_e32 vcc, 0, v81
	s_nop 1
	v_cndmask_b32_e64 v127, -|v81|, v2, vcc
	v_not_b32_e32 v2, v132
	v_cmp_gt_i32_e32 vcc, 0, v132
	s_nop 1
	v_cndmask_b32_e64 v81, -|v132|, v2, vcc
	s_branch .Lsel_disp
.Lsel_m1:
	s_mov_b64 s[6:7], s[0:1]
	s_lshl_b32 s0, 1, s11
	s_or_b32 s13, s0, s10
	s_or_b32 s12, s0, s33
	s_add_i32 s14, s13, -1
	s_add_i32 s15, s12, -1
	v_sub_co_u32_e64 v2, s[8:9], s11, 1
	s_nop 0
	v_readfirstlane_b32 s11, v2
	s_mov_b64 s[4:5], s[42:43]
	s_cmp_lt_u32 s14, 0x7fffff
	s_cselect_b32 s0, 48, 0
	v_mov_b32_e32 v2, s0
	s_cmp_lt_u32 s15, 0x7fffff
	s_cselect_b32 s0, 48, 0
	v_mov_b32_e32 v3, s0
	v_cmp_lt_u32_e64 s[0:1], s14, v127
	v_cmp_lt_u32_e64 s[100:101], s15, v81
	v_cmp_lt_u32_e32 vcc, s14, v4
	v_cndmask_b32_e64 v132, 0, 1, s[0:1]
	v_cndmask_b32_e64 v133, 0, 1, s[100:101]
	v_addc_co_u32_e32 v2, vcc, v2, v132, vcc
	v_cmp_lt_u32_e32 vcc, s15, v6
	v_cmp_lt_u32_e64 s[0:1], s14, v65
	v_cmp_lt_u32_e64 s[100:101], s15, v7
	v_addc_co_u32_e32 v3, vcc, v3, v133, vcc
	v_cmp_lt_u32_e32 vcc, s14, v129
	v_cndmask_b32_e64 v132, 0, 1, s[0:1]
	v_cndmask_b32_e64 v133, 0, 1, s[100:101]
	v_addc_co_u32_e32 v2, vcc, v2, v132, vcc
	v_cmp_lt_u32_e32 vcc, s15, v8
	v_cmp_lt_u32_e64 s[0:1], s14, v70
	v_cmp_lt_u32_e64 s[100:101], s15, v9
	v_addc_co_u32_e32 v3, vcc, v3, v133, vcc
	v_cmp_lt_u32_e32 vcc, s14, v67
	v_cndmask_b32_e64 v132, 0, 1, s[0:1]
	v_cndmask_b32_e64 v133, 0, 1, s[100:101]
	v_addc_co_u32_e32 v2, vcc, v2, v132, vcc
	v_cmp_lt_u32_e32 vcc, s15, v10
	v_cmp_lt_u32_e64 s[0:1], s14, v5
	v_cmp_lt_u32_e64 s[100:101], s15, v11
	v_addc_co_u32_e32 v3, vcc, v3, v133, vcc
	v_cmp_lt_u32_e32 vcc, s14, v69
	v_cndmask_b32_e64 v132, 0, 1, s[0:1]
	v_cndmask_b32_e64 v133, 0, 1, s[100:101]
	v_addc_co_u32_e32 v2, vcc, v2, v132, vcc
	v_cmp_lt_u32_e32 vcc, s15, v12
	v_cmp_lt_u32_e64 s[0:1], s14, v66
	v_cmp_lt_u32_e64 s[100:101], s15, v83
	v_addc_co_u32_e32 v3, vcc, v3, v133, vcc
	v_cmp_lt_u32_e32 vcc, s14, v71
	v_cndmask_b32_e64 v132, 0, 1, s[0:1]
	v_cndmask_b32_e64 v133, 0, 1, s[100:101]
	v_addc_co_u32_e32 v2, vcc, v2, v132, vcc
	v_cmp_lt_u32_e32 vcc, s15, v15
	v_cmp_lt_u32_e64 s[0:1], s14, v128
	v_cmp_lt_u32_e64 s[100:101], s15, v82
	v_addc_co_u32_e32 v3, vcc, v3, v133, vcc
	v_cmp_lt_u32_e32 vcc, s14, v75
	v_cndmask_b32_e64 v132, 0, 1, s[0:1]
	v_cndmask_b32_e64 v133, 0, 1, s[100:101]
	v_addc_co_u32_e32 v2, vcc, v2, v132, vcc
	v_cmp_lt_u32_e32 vcc, s15, v16
	v_cmp_lt_u32_e64 s[0:1], s14, v131
	v_cmp_lt_u32_e64 s[100:101], s15, v85
	v_addc_co_u32_e32 v3, vcc, v3, v133, vcc
	v_cmp_lt_u32_e32 vcc, s14, v68
	v_cndmask_b32_e64 v132, 0, 1, s[0:1]
	v_cndmask_b32_e64 v133, 0, 1, s[100:101]
	v_addc_co_u32_e32 v2, vcc, v2, v132, vcc
	v_cmp_lt_u32_e32 vcc, s15, v13
	v_cmp_lt_u32_e64 s[0:1], s14, v130
	v_cmp_lt_u32_e64 s[100:101], s15, v84
	v_addc_co_u32_e32 v3, vcc, v3, v133, vcc
	v_cmp_lt_u32_e32 vcc, s14, v73
	v_cndmask_b32_e64 v132, 0, 1, s[0:1]
	v_cndmask_b32_e64 v133, 0, 1, s[100:101]
	v_addc_co_u32_e32 v2, vcc, v2, v132, vcc
	v_cmp_lt_u32_e32 vcc, s15, v14
	s_nop 1
	v_addc_co_u32_e32 v3, vcc, v3, v133, vcc
	s_nop 1
	v_add_u32_dpp v2, v2, v2 quad_perm:[1,0,3,2] row_mask:0xf bank_mask:0xf bound_ctrl:1
	v_add_u32_dpp v3, v3, v3 quad_perm:[1,0,3,2] row_mask:0xf bank_mask:0xf bound_ctrl:1
	s_nop 0
	v_add_u32_dpp v2, v2, v2 quad_perm:[2,3,0,1] row_mask:0xf bank_mask:0xf bound_ctrl:1
	v_add_u32_dpp v3, v3, v3 quad_perm:[2,3,0,1] row_mask:0xf bank_mask:0xf bound_ctrl:1
	s_nop 0
	v_add_u32_dpp v2, v2, v2 row_half_mirror row_mask:0xf bank_mask:0xf bound_ctrl:1
	v_add_u32_dpp v3, v3, v3 row_half_mirror row_mask:0xf bank_mask:0xf bound_ctrl:1
	s_nop 0
	v_add_u32_dpp v2, v2, v2 row_mirror row_mask:0xf bank_mask:0xf bound_ctrl:1
	v_add_u32_dpp v3, v3, v3 row_mirror row_mask:0xf bank_mask:0xf bound_ctrl:1
	s_nop 0
	v_add_u32_dpp v2, v2, v2 row_bcast:15 row_mask:0xa bank_mask:0xf
	v_add_u32_dpp v3, v3, v3 row_bcast:15 row_mask:0xa bank_mask:0xf
	s_nop 0
	v_add_u32_dpp v2, v2, v2 row_bcast:31 row_mask:0xc bank_mask:0xf
	v_add_u32_dpp v3, v3, v3 row_bcast:31 row_mask:0xc bank_mask:0xf
	v_readlane_b32 s0, v2, 63
	s_cmpk_gt_i32 s0, 0xff
	s_cselect_b32 s13, s13, s10
	s_cmpk_eq_i32 s0, 0x100
	s_cselect_b64 s[0:1], -1, 0
	s_or_b64 s[0:1], s[6:7], s[0:1]
	s_and_b64 s[6:7], s[6:7], exec
	s_cselect_b32 s10, s10, s13
	v_readlane_b32 s14, v3, 63
	s_cmpk_gt_i32 s14, 0xff
	s_cselect_b32 s12, s12, s33
	s_cmpk_eq_i32 s14, 0x100
	s_cselect_b64 s[6:7], -1, 0
	s_or_b64 s[42:43], s[42:43], s[6:7]
	s_and_b64 s[4:5], s[4:5], exec
	s_cselect_b32 s33, s33, s12
	s_and_b64 s[4:5], s[0:1], s[42:43]
	s_or_b64 s[4:5], s[8:9], s[4:5]
	s_and_b64 vcc, exec, s[4:5]
	s_cbranch_vccz .Lsel_m1
	s_branch .Lsel_exit
; __device__ __forceinline__ void select_item(const Frame& F, int l, int samp, int b, int c, int qg) {
;     ...
;             const unsigned candA = prefixA | (1u << bit), candB = prefixB | (1u << bit), cA1 = candA - 1u, cB1 = candB - 1u; unsigned a4[4] = {0u, 0u, 0u, 0u}, b4[4] = {0u, 0u, 0u, 0u};
; #pragma unroll
;             for (int j = 0; j < 64; ++j) { a4[j & 3] += min(__builtin_elementwise_sub_sat(keyA[j], cA1), 1u); b4[j & 3] += min(__builtin_elementwise_sub_sat(keyB[j], cB1), 1u); }
;             const int cntA = wave_sum_i_dpp((int)((a4[0] + a4[1]) + (a4[2] + a4[3]))), cntB = wave_sum_i_dpp((int)((b4[0] + b4[1]) + (b4[2] + b4[3])));
;             if (!doneA) { if (cntA >= 256) prefixA = candA; if (cntA == 256) doneA = true; }
;             if (!doneB) { if (cntB >= 256) prefixB = candB; if (cntB == 256) doneB = true; }
;         }
.Lsel_m2:
	s_mov_b64 s[6:7], s[0:1]
	s_lshl_b32 s0, 1, s11
	s_or_b32 s13, s0, s10
	s_or_b32 s12, s0, s33
	s_add_i32 s14, s13, -1
	s_add_i32 s15, s12, -1
	v_sub_co_u32_e64 v2, s[8:9], s11, 1
	s_nop 0
	v_readfirstlane_b32 s11, v2
	s_mov_b64 s[4:5], s[42:43]
	s_cmp_lt_u32 s14, 0x7fffff
	s_cselect_b32 s0, 32, 0
	v_mov_b32_e32 v2, s0
	s_cmp_lt_u32 s15, 0x7fffff
	s_cselect_b32 s0, 32, 0
	v_mov_b32_e32 v3, s0
	v_cmp_lt_u32_e64 s[0:1], s14, v127
	v_cmp_lt_u32_e64 s[100:101], s15, v81
	v_cmp_lt_u32_e32 vcc, s14, v4
	v_cndmask_b32_e64 v132, 0, 1, s[0:1]
	v_cndmask_b32_e64 v133, 0, 1, s[100:101]
	v_addc_co_u32_e32 v2, vcc, v2, v132, vcc
	v_cmp_lt_u32_e32 vcc, s15, v6
	v_cmp_lt_u32_e64 s[0:1], s14, v65
	v_cmp_lt_u32_e64 s[100:101], s15, v7
	v_addc_co_u32_e32 v3, vcc, v3, v133, vcc
	v_cmp_lt_u32_e32 vcc, s14, v129
	v_cndmask_b32_e64 v132, 0, 1, s[0:1]
	v_cndmask_b32_e64 v133, 0, 1, s[100:101]
	v_addc_co_u32_e32 v2, vcc, v2, v132, vcc
	v_cmp_lt_u32_e32 vcc, s15, v8
	v_cmp_lt_u32_e64 s[0:1], s14, v70
	v_cmp_lt_u32_e64 s[100:101], s15, v9
	v_addc_co_u32_e32 v3, vcc, v3, v133, vcc
	v_cmp_lt_u32_e32 vcc, s14, v67
	v_cndmask_b32_e64 v132, 0, 1, s[0:1]
	v_cndmask_b32_e64 v133, 0, 1, s[100:101]
	v_addc_co_u32_e32 v2, vcc, v2, v132, vcc
	v_cmp_lt_u32_e32 vcc, s15, v10
	v_cmp_lt_u32_e64 s[0:1], s14, v5
	v_cmp_lt_u32_e64 s[100:101], s15, v11
	v_addc_co_u32_e32 v3, vcc, v3, v133, vcc
	v_cmp_lt_u32_e32 vcc, s14, v69
	v_cndmask_b32_e64 v132, 0, 1, s[0:1]
	v_cndmask_b32_e64 v133, 0, 1, s[100:101]
	v_addc_co_u32_e32 v2, vcc, v2, v132, vcc
	v_cmp_lt_u32_e32 vcc, s15, v12
	v_cmp_lt_u32_e64 s[0:1], s14, v66
	v_cmp_lt_u32_e64 s[100:101], s15, v17
	v_addc_co_u32_e32 v3, vcc, v3, v133, vcc
	v_cmp_lt_u32_e32 vcc, s14, v71
	v_cndmask_b32_e64 v132, 0, 1, s[0:1]
	v_cndmask_b32_e64 v133, 0, 1, s[100:101]
	v_addc_co_u32_e32 v2, vcc, v2, v132, vcc
	v_cmp_lt_u32_e32 vcc, s15, v18
	v_cmp_lt_u32_e64 s[0:1], s14, v79
	v_cmp_lt_u32_e64 s[100:101], s15, v19
	v_addc_co_u32_e32 v3, vcc, v3, v133, vcc
	v_cmp_lt_u32_e32 vcc, s14, v72
	v_cndmask_b32_e64 v132, 0, 1, s[0:1]
	v_cndmask_b32_e64 v133, 0, 1, s[100:101]
	v_addc_co_u32_e32 v2, vcc, v2, v132, vcc
	v_cmp_lt_u32_e32 vcc, s15, v20
	v_cmp_lt_u32_e64 s[0:1], s14, v76
	v_cmp_lt_u32_e64 s[100:101], s15, v25
	v_addc_co_u32_e32 v3, vcc, v3, v133, vcc
	v_cmp_lt_u32_e32 vcc, s14, v74
	v_cndmask_b32_e64 v132, 0, 1, s[0:1]
	v_cndmask_b32_e64 v133, 0, 1, s[100:101]
	v_addc_co_u32_e32 v2, vcc, v2, v132, vcc
	v_cmp_lt_u32_e32 vcc, s15, v26
	v_cmp_lt_u32_e64 s[0:1], s14, v78
	v_cmp_lt_u32_e64 s[100:101], s15, v27
	v_addc_co_u32_e32 v3, vcc, v3, v133, vcc
	v_cmp_lt_u32_e32 vcc, s14, v92
	v_cndmask_b32_e64 v132, 0, 1, s[0:1]
	v_cndmask_b32_e64 v133, 0, 1, s[100:101]
	v_addc_co_u32_e32 v2, vcc, v2, v132, vcc
	v_cmp_lt_u32_e32 vcc, s15, v28
	v_cmp_lt_u32_e64 s[0:1], s14, v86
	v_cmp_lt_u32_e64 s[100:101], s15, v83
	v_addc_co_u32_e32 v3, vcc, v3, v133, vcc
	v_cmp_lt_u32_e32 vcc, s14, v89
	v_cndmask_b32_e64 v132, 0, 1, s[0:1]
	v_cndmask_b32_e64 v133, 0, 1, s[100:101]
	v_addc_co_u32_e32 v2, vcc, v2, v132, vcc
	v_cmp_lt_u32_e32 vcc, s15, v15
	v_cmp_lt_u32_e64 s[0:1], s14, v88
	v_cmp_lt_u32_e64 s[100:101], s15, v23
	v_addc_co_u32_e32 v3, vcc, v3, v133, vcc
	v_cmp_lt_u32_e32 vcc, s14, v91
	v_cndmask_b32_e64 v132, 0, 1, s[0:1]
	v_cndmask_b32_e64 v133, 0, 1, s[100:101]
	v_addc_co_u32_e32 v2, vcc, v2, v132, vcc
	v_cmp_lt_u32_e32 vcc, s15, v31
	v_cmp_lt_u32_e64 s[0:1], s14, v128
	v_cmp_lt_u32_e64 s[100:101], s15, v82
	v_addc_co_u32_e32 v3, vcc, v3, v133, vcc
	v_cmp_lt_u32_e32 vcc, s14, v75
	v_cndmask_b32_e64 v132, 0, 1, s[0:1]
	v_cndmask_b32_e64 v133, 0, 1, s[100:101]
	v_addc_co_u32_e32 v2, vcc, v2, v132, vcc
	v_cmp_lt_u32_e32 vcc, s15, v16
	v_cmp_lt_u32_e64 s[0:1], s14, v87
	v_cmp_lt_u32_e64 s[100:101], s15, v24
	v_addc_co_u32_e32 v3, vcc, v3, v133, vcc
	v_cmp_lt_u32_e32 vcc, s14, v95
	v_cndmask_b32_e64 v132, 0, 1, s[0:1]
	v_cndmask_b32_e64 v133, 0, 1, s[100:101]
	v_addc_co_u32_e32 v2, vcc, v2, v132, vcc
	v_cmp_lt_u32_e32 vcc, s15, v32
	v_cmp_lt_u32_e64 s[0:1], s14, v131
	v_cmp_lt_u32_e64 s[100:101], s15, v85
	v_addc_co_u32_e32 v3, vcc, v3, v133, vcc
	v_cmp_lt_u32_e32 vcc, s14, v68
	v_cndmask_b32_e64 v132, 0, 1, s[0:1]
	v_cndmask_b32_e64 v133, 0, 1, s[100:101]
	v_addc_co_u32_e32 v2, vcc, v2, v132, vcc
	v_cmp_lt_u32_e32 vcc, s15, v13
	v_cmp_lt_u32_e64 s[0:1], s14, v77
	v_cmp_lt_u32_e64 s[100:101], s15, v21
	v_addc_co_u32_e32 v3, vcc, v3, v133, vcc
	v_cmp_lt_u32_e32 vcc, s14, v90
	v_cndmask_b32_e64 v132, 0, 1, s[0:1]
	v_cndmask_b32_e64 v133, 0, 1, s[100:101]
	v_addc_co_u32_e32 v2, vcc, v2, v132, vcc
	v_cmp_lt_u32_e32 vcc, s15, v29
	v_cmp_lt_u32_e64 s[0:1], s14, v130
	v_cmp_lt_u32_e64 s[100:101], s15, v84
	v_addc_co_u32_e32 v3, vcc, v3, v133, vcc
	v_cmp_lt_u32_e32 vcc, s14, v73
	v_cndmask_b32_e64 v132, 0, 1, s[0:1]
	v_cndmask_b32_e64 v133, 0, 1, s[100:101]
	v_addc_co_u32_e32 v2, vcc, v2, v132, vcc
	v_cmp_lt_u32_e32 vcc, s15, v14
	v_cmp_lt_u32_e64 s[0:1], s14, v80
	v_cmp_lt_u32_e64 s[100:101], s15, v22
	v_addc_co_u32_e32 v3, vcc, v3, v133, vcc
	v_cmp_lt_u32_e32 vcc, s14, v93
	v_cndmask_b32_e64 v132, 0, 1, s[0:1]
	v_cndmask_b32_e64 v133, 0, 1, s[100:101]
	v_addc_co_u32_e32 v2, vcc, v2, v132, vcc
	v_cmp_lt_u32_e32 vcc, s15, v30
	s_nop 1
	v_addc_co_u32_e32 v3, vcc, v3, v133, vcc
	s_nop 1
	v_add_u32_dpp v2, v2, v2 quad_perm:[1,0,3,2] row_mask:0xf bank_mask:0xf bound_ctrl:1
	v_add_u32_dpp v3, v3, v3 quad_perm:[1,0,3,2] row_mask:0xf bank_mask:0xf bound_ctrl:1
	s_nop 0
	v_add_u32_dpp v2, v2, v2 quad_perm:[2,3,0,1] row_mask:0xf bank_mask:0xf bound_ctrl:1
	v_add_u32_dpp v3, v3, v3 quad_perm:[2,3,0,1] row_mask:0xf bank_mask:0xf bound_ctrl:1
	s_nop 0
	v_add_u32_dpp v2, v2, v2 row_half_mirror row_mask:0xf bank_mask:0xf bound_ctrl:1
	v_add_u32_dpp v3, v3, v3 row_half_mirror row_mask:0xf bank_mask:0xf bound_ctrl:1
	s_nop 0
	v_add_u32_dpp v2, v2, v2 row_mirror row_mask:0xf bank_mask:0xf bound_ctrl:1
	v_add_u32_dpp v3, v3, v3 row_mirror row_mask:0xf bank_mask:0xf bound_ctrl:1
	s_nop 0
	v_add_u32_dpp v2, v2, v2 row_bcast:15 row_mask:0xa bank_mask:0xf
	v_add_u32_dpp v3, v3, v3 row_bcast:15 row_mask:0xa bank_mask:0xf
	s_nop 0
	v_add_u32_dpp v2, v2, v2 row_bcast:31 row_mask:0xc bank_mask:0xf
	v_add_u32_dpp v3, v3, v3 row_bcast:31 row_mask:0xc bank_mask:0xf
	v_readlane_b32 s0, v2, 63
	s_cmpk_gt_i32 s0, 0xff
	s_cselect_b32 s13, s13, s10
	s_cmpk_eq_i32 s0, 0x100
	s_cselect_b64 s[0:1], -1, 0
	s_or_b64 s[0:1], s[6:7], s[0:1]
	s_and_b64 s[6:7], s[6:7], exec
	s_cselect_b32 s10, s10, s13
	v_readlane_b32 s14, v3, 63
	s_cmpk_gt_i32 s14, 0xff
	s_cselect_b32 s12, s12, s33
	s_cmpk_eq_i32 s14, 0x100
	s_cselect_b64 s[6:7], -1, 0
	s_or_b64 s[42:43], s[42:43], s[6:7]
	s_and_b64 s[4:5], s[4:5], exec
	s_cselect_b32 s33, s33, s12
	s_and_b64 s[4:5], s[0:1], s[42:43]
	s_or_b64 s[4:5], s[8:9], s[4:5]
	s_and_b64 vcc, exec, s[4:5]
	s_cbranch_vccz .Lsel_m2
	s_branch .Lsel_exit
; __device__ __forceinline__ void select_item(const Frame& F, int l, int samp, int b, int c, int qg) {
;     ...
;             const unsigned candA = prefixA | (1u << bit), candB = prefixB | (1u << bit), cA1 = candA - 1u, cB1 = candB - 1u; unsigned a4[4] = {0u, 0u, 0u, 0u}, b4[4] = {0u, 0u, 0u, 0u};
; #pragma unroll
;             for (int j = 0; j < 64; ++j) { a4[j & 3] += min(__builtin_elementwise_sub_sat(keyA[j], cA1), 1u); b4[j & 3] += min(__builtin_elementwise_sub_sat(keyB[j], cB1), 1u); }
;             const int cntA = wave_sum_i_dpp((int)((a4[0] + a4[1]) + (a4[2] + a4[3]))), cntB = wave_sum_i_dpp((int)((b4[0] + b4[1]) + (b4[2] + b4[3])));
;             if (!doneA) { if (cntA >= 256) prefixA = candA; if (cntA == 256) doneA = true; }
;             if (!doneB) { if (cntB >= 256) prefixB = candB; if (cntB == 256) doneB = true; }
;         }
.Lsel_m3:
	s_mov_b64 s[6:7], s[0:1]
	s_lshl_b32 s0, 1, s11
	s_or_b32 s13, s0, s10
	s_or_b32 s12, s0, s33
	s_add_i32 s14, s13, -1
	s_add_i32 s15, s12, -1
	v_sub_co_u32_e64 v2, s[8:9], s11, 1
	s_nop 0
	v_readfirstlane_b32 s11, v2
	s_mov_b64 s[4:5], s[42:43]
	s_cmp_lt_u32 s14, 0x7fffff
	s_cselect_b32 s0, 16, 0
	v_mov_b32_e32 v2, s0
	s_cmp_lt_u32 s15, 0x7fffff
	s_cselect_b32 s0, 16, 0
	v_mov_b32_e32 v3, s0
	v_cmp_lt_u32_e64 s[0:1], s14, v127
	v_cmp_lt_u32_e64 s[100:101], s15, v81
	v_cmp_lt_u32_e32 vcc, s14, v4
	v_cndmask_b32_e64 v132, 0, 1, s[0:1]
	v_cndmask_b32_e64 v133, 0, 1, s[100:101]
	v_addc_co_u32_e32 v2, vcc, v2, v132, vcc
	v_cmp_lt_u32_e32 vcc, s15, v6
	v_cmp_lt_u32_e64 s[0:1], s14, v65
	v_cmp_lt_u32_e64 s[100:101], s15, v7
	v_addc_co_u32_e32 v3, vcc, v3, v133, vcc
	v_cmp_lt_u32_e32 vcc, s14, v129
	v_cndmask_b32_e64 v132, 0, 1, s[0:1]
	v_cndmask_b32_e64 v133, 0, 1, s[100:101]
	v_addc_co_u32_e32 v2, vcc, v2, v132, vcc
	v_cmp_lt_u32_e32 vcc, s15, v8
	v_cmp_lt_u32_e64 s[0:1], s14, v70
	v_cmp_lt_u32_e64 s[100:101], s15, v9
	v_addc_co_u32_e32 v3, vcc, v3, v133, vcc
	v_cmp_lt_u32_e32 vcc, s14, v67
	v_cndmask_b32_e64 v132, 0, 1, s[0:1]
	v_cndmask_b32_e64 v133, 0, 1, s[100:101]
	v_addc_co_u32_e32 v2, vcc, v2, v132, vcc
	v_cmp_lt_u32_e32 vcc, s15, v10
	v_cmp_lt_u32_e64 s[0:1], s14, v5
	v_cmp_lt_u32_e64 s[100:101], s15, v11
	v_addc_co_u32_e32 v3, vcc, v3, v133, vcc
	v_cmp_lt_u32_e32 vcc, s14, v69
	v_cndmask_b32_e64 v132, 0, 1, s[0:1]
	v_cndmask_b32_e64 v133, 0, 1, s[100:101]
	v_addc_co_u32_e32 v2, vcc, v2, v132, vcc
	v_cmp_lt_u32_e32 vcc, s15, v12
	v_cmp_lt_u32_e64 s[0:1], s14, v66
	v_cmp_lt_u32_e64 s[100:101], s15, v17
	v_addc_co_u32_e32 v3, vcc, v3, v133, vcc
	v_cmp_lt_u32_e32 vcc, s14, v71
	v_cndmask_b32_e64 v132, 0, 1, s[0:1]
	v_cndmask_b32_e64 v133, 0, 1, s[100:101]
	v_addc_co_u32_e32 v2, vcc, v2, v132, vcc
	v_cmp_lt_u32_e32 vcc, s15, v18
	v_cmp_lt_u32_e64 s[0:1], s14, v79
	v_cmp_lt_u32_e64 s[100:101], s15, v19
	v_addc_co_u32_e32 v3, vcc, v3, v133, vcc
	v_cmp_lt_u32_e32 vcc, s14, v72
	v_cndmask_b32_e64 v132, 0, 1, s[0:1]
	v_cndmask_b32_e64 v133, 0, 1, s[100:101]
	v_addc_co_u32_e32 v2, vcc, v2, v132, vcc
	v_cmp_lt_u32_e32 vcc, s15, v20
	v_cmp_lt_u32_e64 s[0:1], s14, v76
	v_cmp_lt_u32_e64 s[100:101], s15, v25
	v_addc_co_u32_e32 v3, vcc, v3, v133, vcc
	v_cmp_lt_u32_e32 vcc, s14, v74
	v_cndmask_b32_e64 v132, 0, 1, s[0:1]
	v_cndmask_b32_e64 v133, 0, 1, s[100:101]
	v_addc_co_u32_e32 v2, vcc, v2, v132, vcc
	v_cmp_lt_u32_e32 vcc, s15, v26
	v_cmp_lt_u32_e64 s[0:1], s14, v78
	v_cmp_lt_u32_e64 s[100:101], s15, v27
	v_addc_co_u32_e32 v3, vcc, v3, v133, vcc
	v_cmp_lt_u32_e32 vcc, s14, v92
	v_cndmask_b32_e64 v132, 0, 1, s[0:1]
	v_cndmask_b32_e64 v133, 0, 1, s[100:101]
	v_addc_co_u32_e32 v2, vcc, v2, v132, vcc
	v_cmp_lt_u32_e32 vcc, s15, v28
	v_cmp_lt_u32_e64 s[0:1], s14, v86
	v_cmp_lt_u32_e64 s[100:101], s15, v33
	v_addc_co_u32_e32 v3, vcc, v3, v133, vcc
	v_cmp_lt_u32_e32 vcc, s14, v89
	v_cndmask_b32_e64 v132, 0, 1, s[0:1]
	v_cndmask_b32_e64 v133, 0, 1, s[100:101]
	v_addc_co_u32_e32 v2, vcc, v2, v132, vcc
	v_cmp_lt_u32_e32 vcc, s15, v34
	v_cmp_lt_u32_e64 s[0:1], s14, v88
	v_cmp_lt_u32_e64 s[100:101], s15, v35
	v_addc_co_u32_e32 v3, vcc, v3, v133, vcc
	v_cmp_lt_u32_e32 vcc, s14, v91
	v_cndmask_b32_e64 v132, 0, 1, s[0:1]
	v_cndmask_b32_e64 v133, 0, 1, s[100:101]
	v_addc_co_u32_e32 v2, vcc, v2, v132, vcc
	v_cmp_lt_u32_e32 vcc, s15, v36
	v_cmp_lt_u32_e64 s[0:1], s14, v100
	v_cmp_lt_u32_e64 s[100:101], s15, v41
	v_addc_co_u32_e32 v3, vcc, v3, v133, vcc
	v_cmp_lt_u32_e32 vcc, s14, v94
	v_cndmask_b32_e64 v132, 0, 1, s[0:1]
	v_cndmask_b32_e64 v133, 0, 1, s[100:101]
	v_addc_co_u32_e32 v2, vcc, v2, v132, vcc
	v_cmp_lt_u32_e32 vcc, s15, v42
	v_cmp_lt_u32_e64 s[0:1], s14, v97
	v_cmp_lt_u32_e64 s[100:101], s15, v43
	v_addc_co_u32_e32 v3, vcc, v3, v133, vcc
	v_cmp_lt_u32_e32 vcc, s14, v96
	v_cndmask_b32_e64 v132, 0, 1, s[0:1]
	v_cndmask_b32_e64 v133, 0, 1, s[100:101]
	v_addc_co_u32_e32 v2, vcc, v2, v132, vcc
	v_cmp_lt_u32_e32 vcc, s15, v44
	v_cmp_lt_u32_e64 s[0:1], s14, v99
	v_cmp_lt_u32_e64 s[100:101], s15, v83
	v_addc_co_u32_e32 v3, vcc, v3, v133, vcc
	v_cmp_lt_u32_e32 vcc, s14, v108
	v_cndmask_b32_e64 v132, 0, 1, s[0:1]
	v_cndmask_b32_e64 v133, 0, 1, s[100:101]
	v_addc_co_u32_e32 v2, vcc, v2, v132, vcc
	v_cmp_lt_u32_e32 vcc, s15, v15
	v_cmp_lt_u32_e64 s[0:1], s14, v102
	v_cmp_lt_u32_e64 s[100:101], s15, v23
	v_addc_co_u32_e32 v3, vcc, v3, v133, vcc
	v_cmp_lt_u32_e32 vcc, s14, v105
	v_cndmask_b32_e64 v132, 0, 1, s[0:1]
	v_cndmask_b32_e64 v133, 0, 1, s[100:101]
	v_addc_co_u32_e32 v2, vcc, v2, v132, vcc
	v_cmp_lt_u32_e32 vcc, s15, v31
	v_cmp_lt_u32_e64 s[0:1], s14, v104
	v_cmp_lt_u32_e64 s[100:101], s15, v39
	v_addc_co_u32_e32 v3, vcc, v3, v133, vcc
; __device__ __forceinline__ void select_item(const Frame& F, int l, int samp, int b, int c, int qg) {
;     ...
;             const unsigned candA = prefixA | (1u << bit), candB = prefixB | (1u << bit), cA1 = candA - 1u, cB1 = candB - 1u; unsigned a4[4] = {0u, 0u, 0u, 0u}, b4[4] = {0u, 0u, 0u, 0u};
; #pragma unroll
;             for (int j = 0; j < 64; ++j) { a4[j & 3] += min(__builtin_elementwise_sub_sat(keyA[j], cA1), 1u); b4[j & 3] += min(__builtin_elementwise_sub_sat(keyB[j], cB1), 1u); }
;             const int cntA = wave_sum_i_dpp((int)((a4[0] + a4[1]) + (a4[2] + a4[3]))), cntB = wave_sum_i_dpp((int)((b4[0] + b4[1]) + (b4[2] + b4[3])));
;             if (!doneA) { if (cntA >= 256) prefixA = candA; if (cntA == 256) doneA = true; }
;             if (!doneB) { if (cntB >= 256) prefixB = candB; if (cntB == 256) doneB = true; }
;         }
	v_cmp_lt_u32_e32 vcc, s14, v107
	v_cndmask_b32_e64 v132, 0, 1, s[0:1]
	v_cndmask_b32_e64 v133, 0, 1, s[100:101]
	v_addc_co_u32_e32 v2, vcc, v2, v132, vcc
	v_cmp_lt_u32_e32 vcc, s15, v47
	v_cmp_lt_u32_e64 s[0:1], s14, v128
	v_cmp_lt_u32_e64 s[100:101], s15, v82
	v_addc_co_u32_e32 v3, vcc, v3, v133, vcc
	v_cmp_lt_u32_e32 vcc, s14, v75
	v_cndmask_b32_e64 v132, 0, 1, s[0:1]
	v_cndmask_b32_e64 v133, 0, 1, s[100:101]
	v_addc_co_u32_e32 v2, vcc, v2, v132, vcc
	v_cmp_lt_u32_e32 vcc, s15, v16
	v_cmp_lt_u32_e64 s[0:1], s14, v87
	v_cmp_lt_u32_e64 s[100:101], s15, v24
	v_addc_co_u32_e32 v3, vcc, v3, v133, vcc
	v_cmp_lt_u32_e32 vcc, s14, v95
	v_cndmask_b32_e64 v132, 0, 1, s[0:1]
	v_cndmask_b32_e64 v133, 0, 1, s[100:101]
	v_addc_co_u32_e32 v2, vcc, v2, v132, vcc
	v_cmp_lt_u32_e32 vcc, s15, v32
	v_cmp_lt_u32_e64 s[0:1], s14, v103
	v_cmp_lt_u32_e64 s[100:101], s15, v40
	v_addc_co_u32_e32 v3, vcc, v3, v133, vcc
	v_cmp_lt_u32_e32 vcc, s14, v111
	v_cndmask_b32_e64 v132, 0, 1, s[0:1]
	v_cndmask_b32_e64 v133, 0, 1, s[100:101]
	v_addc_co_u32_e32 v2, vcc, v2, v132, vcc
	v_cmp_lt_u32_e32 vcc, s15, v48
	v_cmp_lt_u32_e64 s[0:1], s14, v131
	v_cmp_lt_u32_e64 s[100:101], s15, v85
	v_addc_co_u32_e32 v3, vcc, v3, v133, vcc
	v_cmp_lt_u32_e32 vcc, s14, v68
	v_cndmask_b32_e64 v132, 0, 1, s[0:1]
	v_cndmask_b32_e64 v133, 0, 1, s[100:101]
	v_addc_co_u32_e32 v2, vcc, v2, v132, vcc
	v_cmp_lt_u32_e32 vcc, s15, v13
	v_cmp_lt_u32_e64 s[0:1], s14, v77
	v_cmp_lt_u32_e64 s[100:101], s15, v21
	v_addc_co_u32_e32 v3, vcc, v3, v133, vcc
	v_cmp_lt_u32_e32 vcc, s14, v90
	v_cndmask_b32_e64 v132, 0, 1, s[0:1]
	v_cndmask_b32_e64 v133, 0, 1, s[100:101]
	v_addc_co_u32_e32 v2, vcc, v2, v132, vcc
	v_cmp_lt_u32_e32 vcc, s15, v29
	v_cmp_lt_u32_e64 s[0:1], s14, v98
	v_cmp_lt_u32_e64 s[100:101], s15, v37
	v_addc_co_u32_e32 v3, vcc, v3, v133, vcc
	v_cmp_lt_u32_e32 vcc, s14, v106
	v_cndmask_b32_e64 v132, 0, 1, s[0:1]
	v_cndmask_b32_e64 v133, 0, 1, s[100:101]
	v_addc_co_u32_e32 v2, vcc, v2, v132, vcc
	v_cmp_lt_u32_e32 vcc, s15, v45
	v_cmp_lt_u32_e64 s[0:1], s14, v130
	v_cmp_lt_u32_e64 s[100:101], s15, v84
	v_addc_co_u32_e32 v3, vcc, v3, v133, vcc
	v_cmp_lt_u32_e32 vcc, s14, v73
	v_cndmask_b32_e64 v132, 0, 1, s[0:1]
	v_cndmask_b32_e64 v133, 0, 1, s[100:101]
	v_addc_co_u32_e32 v2, vcc, v2, v132, vcc
	v_cmp_lt_u32_e32 vcc, s15, v14
	v_cmp_lt_u32_e64 s[0:1], s14, v80
	v_cmp_lt_u32_e64 s[100:101], s15, v22
	v_addc_co_u32_e32 v3, vcc, v3, v133, vcc
	v_cmp_lt_u32_e32 vcc, s14, v93
	v_cndmask_b32_e64 v132, 0, 1, s[0:1]
	v_cndmask_b32_e64 v133, 0, 1, s[100:101]
	v_addc_co_u32_e32 v2, vcc, v2, v132, vcc
	v_cmp_lt_u32_e32 vcc, s15, v30
	v_cmp_lt_u32_e64 s[0:1], s14, v101
	v_cmp_lt_u32_e64 s[100:101], s15, v38
	v_addc_co_u32_e32 v3, vcc, v3, v133, vcc
	v_cmp_lt_u32_e32 vcc, s14, v109
	v_cndmask_b32_e64 v132, 0, 1, s[0:1]
	v_cndmask_b32_e64 v133, 0, 1, s[100:101]
	v_addc_co_u32_e32 v2, vcc, v2, v132, vcc
	v_cmp_lt_u32_e32 vcc, s15, v46
	s_nop 1
	v_addc_co_u32_e32 v3, vcc, v3, v133, vcc
	s_nop 1
	v_add_u32_dpp v2, v2, v2 quad_perm:[1,0,3,2] row_mask:0xf bank_mask:0xf bound_ctrl:1
	v_add_u32_dpp v3, v3, v3 quad_perm:[1,0,3,2] row_mask:0xf bank_mask:0xf bound_ctrl:1
	s_nop 0
	v_add_u32_dpp v2, v2, v2 quad_perm:[2,3,0,1] row_mask:0xf bank_mask:0xf bound_ctrl:1
	v_add_u32_dpp v3, v3, v3 quad_perm:[2,3,0,1] row_mask:0xf bank_mask:0xf bound_ctrl:1
	s_nop 0
	v_add_u32_dpp v2, v2, v2 row_half_mirror row_mask:0xf bank_mask:0xf bound_ctrl:1
	v_add_u32_dpp v3, v3, v3 row_half_mirror row_mask:0xf bank_mask:0xf bound_ctrl:1
	s_nop 0
	v_add_u32_dpp v2, v2, v2 row_mirror row_mask:0xf bank_mask:0xf bound_ctrl:1
	v_add_u32_dpp v3, v3, v3 row_mirror row_mask:0xf bank_mask:0xf bound_ctrl:1
	s_nop 0
	v_add_u32_dpp v2, v2, v2 row_bcast:15 row_mask:0xa bank_mask:0xf
	v_add_u32_dpp v3, v3, v3 row_bcast:15 row_mask:0xa bank_mask:0xf
	s_nop 0
	v_add_u32_dpp v2, v2, v2 row_bcast:31 row_mask:0xc bank_mask:0xf
	v_add_u32_dpp v3, v3, v3 row_bcast:31 row_mask:0xc bank_mask:0xf
	v_readlane_b32 s0, v2, 63
	s_cmpk_gt_i32 s0, 0xff
	s_cselect_b32 s13, s13, s10
	s_cmpk_eq_i32 s0, 0x100
	s_cselect_b64 s[0:1], -1, 0
	s_or_b64 s[0:1], s[6:7], s[0:1]
	s_and_b64 s[6:7], s[6:7], exec
	s_cselect_b32 s10, s10, s13
	v_readlane_b32 s14, v3, 63
	s_cmpk_gt_i32 s14, 0xff
	s_cselect_b32 s12, s12, s33
	s_cmpk_eq_i32 s14, 0x100
	s_cselect_b64 s[6:7], -1, 0
	s_or_b64 s[42:43], s[42:43], s[6:7]
	s_and_b64 s[4:5], s[4:5], exec
	s_cselect_b32 s33, s33, s12
	s_and_b64 s[4:5], s[0:1], s[42:43]
	s_or_b64 s[4:5], s[8:9], s[4:5]
	s_and_b64 vcc, exec, s[4:5]
	s_cbranch_vccz .Lsel_m3
	s_branch .Lsel_exit
.Lsel_disp:
	s_cmp_eq_u32 s98, 0
	s_cbranch_scc1 .Lsel_m1
	s_cmp_eq_u32 s98, 1
	s_cbranch_scc1 .Lsel_m2
	s_cmp_eq_u32 s98, 2
	s_cbranch_scc1 .Lsel_m3

.Lsel_exit:
	v_writelane_b32 v254, s70, 29
	s_xor_b64 s[0:1], s[0:1], -1
	v_mov_b32_e32 v132, s10
	v_writelane_b32 v254, s71, 30
	s_andn2_b64 vcc, exec, s[0:1]
	s_mov_b64 s[0:1], -1
	s_cbranch_vccnz .LBB0_1439
	v_cmp_gt_u32_e32 vcc, v130, v132
	s_mov_b32 s8, 0
	s_nop 0
	v_cndmask_b32_e64 v2, 0, 1, vcc
	v_cmp_gt_u32_e32 vcc, v131, v132
	s_nop 1
	v_addc_co_u32_e32 v2, vcc, 0, v2, vcc
	v_cmp_gt_u32_e32 vcc, v129, v132
	s_nop 1
	v_cndmask_b32_e64 v3, 0, 1, vcc
	v_cmp_gt_u32_e32 vcc, v128, v132
	s_nop 1
	v_addc_co_u32_e32 v2, vcc, v2, v3, vcc
	v_cmp_gt_u32_e32 vcc, v127, v132
	s_nop 1
	v_cndmask_b32_e64 v3, 0, 1, vcc
	v_cmp_gt_u32_e32 vcc, v65, v132
	s_nop 1
	v_addc_co_u32_e32 v2, vcc, v2, v3, vcc
	v_cmp_gt_u32_e32 vcc, v4, v132
	s_nop 1
	v_cndmask_b32_e64 v3, 0, 1, vcc
	v_cmp_gt_u32_e32 vcc, v67, v132
	s_nop 1
	v_addc_co_u32_e32 v2, vcc, v2, v3, vcc
	v_cmp_gt_u32_e32 vcc, v5, v132
	s_nop 1
	v_cndmask_b32_e64 v3, 0, 1, vcc
	v_cmp_gt_u32_e32 vcc, v69, v132
	s_nop 1
	v_addc_co_u32_e32 v2, vcc, v2, v3, vcc
	v_cmp_gt_u32_e32 vcc, v66, v132
	s_nop 1
	v_cndmask_b32_e64 v3, 0, 1, vcc
	v_cmp_gt_u32_e32 vcc, v71, v132
	s_nop 1
	v_addc_co_u32_e32 v2, vcc, v2, v3, vcc
	v_cmp_gt_u32_e32 vcc, v68, v132
	s_nop 1
	v_cndmask_b32_e64 v3, 0, 1, vcc
	v_cmp_gt_u32_e32 vcc, v73, v132
	s_nop 1
	v_addc_co_u32_e32 v2, vcc, v2, v3, vcc
	v_cmp_gt_u32_e32 vcc, v70, v132
	s_nop 1
	v_cndmask_b32_e64 v3, 0, 1, vcc
	v_cmp_gt_u32_e32 vcc, v75, v132
	s_nop 1
	v_addc_co_u32_e32 v2, vcc, v2, v3, vcc
	v_cmp_gt_u32_e32 vcc, v72, v132
	s_nop 1
	v_cndmask_b32_e64 v3, 0, 1, vcc
	v_cmp_gt_u32_e32 vcc, v76, v132
	s_nop 1
	v_addc_co_u32_e32 v2, vcc, v2, v3, vcc
	v_cmp_gt_u32_e32 vcc, v74, v132
	s_nop 1
	v_cndmask_b32_e64 v3, 0, 1, vcc
	v_cmp_gt_u32_e32 vcc, v78, v132
	s_nop 1
	v_addc_co_u32_e32 v2, vcc, v2, v3, vcc
	v_cmp_gt_u32_e32 vcc, v77, v132
	s_nop 1
	v_cndmask_b32_e64 v3, 0, 1, vcc
	v_cmp_gt_u32_e32 vcc, v80, v132
	s_nop 1
	v_addc_co_u32_e32 v2, vcc, v2, v3, vcc
	v_cmp_gt_u32_e32 vcc, v79, v132
	s_nop 1
	v_cndmask_b32_e64 v3, 0, 1, vcc
	v_cmp_gt_u32_e32 vcc, v87, v132
	s_nop 1
	v_addc_co_u32_e32 v2, vcc, v2, v3, vcc
	v_cmp_gt_u32_e32 vcc, v86, v132
	s_nop 1
	v_cndmask_b32_e64 v3, 0, 1, vcc
	v_cmp_gt_u32_e32 vcc, v89, v132
	s_nop 1
	v_addc_co_u32_e32 v2, vcc, v2, v3, vcc
	v_cmp_gt_u32_e32 vcc, v88, v132
	s_nop 1
	v_cndmask_b32_e64 v3, 0, 1, vcc
	v_cmp_gt_u32_e32 vcc, v91, v132
	s_nop 1
	v_addc_co_u32_e32 v2, vcc, v2, v3, vcc
	v_cmp_gt_u32_e32 vcc, v90, v132
	s_nop 1
	v_cndmask_b32_e64 v3, 0, 1, vcc
	v_cmp_gt_u32_e32 vcc, v93, v132
	s_nop 1
	v_addc_co_u32_e32 v2, vcc, v2, v3, vcc
	v_cmp_gt_u32_e32 vcc, v92, v132
	s_nop 1
	v_cndmask_b32_e64 v3, 0, 1, vcc
	v_cmp_gt_u32_e32 vcc, v95, v132
	s_nop 1
	v_addc_co_u32_e32 v2, vcc, v2, v3, vcc
	v_cmp_gt_u32_e32 vcc, v94, v132
	s_nop 1
	v_cndmask_b32_e64 v3, 0, 1, vcc
	v_cmp_gt_u32_e32 vcc, v97, v132
	s_nop 1
	v_addc_co_u32_e32 v2, vcc, v2, v3, vcc
	v_cmp_gt_u32_e32 vcc, v96, v132
	s_nop 1
	v_cndmask_b32_e64 v3, 0, 1, vcc
	v_cmp_gt_u32_e32 vcc, v99, v132
	s_nop 1
	v_addc_co_u32_e32 v2, vcc, v2, v3, vcc
	v_cmp_gt_u32_e32 vcc, v98, v132
	s_nop 1
	v_cndmask_b32_e64 v3, 0, 1, vcc
	v_cmp_gt_u32_e32 vcc, v101, v132
	s_nop 1
	v_addc_co_u32_e32 v2, vcc, v2, v3, vcc
	v_cmp_gt_u32_e32 vcc, v100, v132
	s_nop 1
	v_cndmask_b32_e64 v3, 0, 1, vcc
	v_cmp_gt_u32_e32 vcc, v103, v132
	s_nop 1
	v_addc_co_u32_e32 v2, vcc, v2, v3, vcc
	v_cmp_gt_u32_e32 vcc, v102, v132
	s_nop 1
	v_cndmask_b32_e64 v3, 0, 1, vcc
	v_cmp_gt_u32_e32 vcc, v105, v132
	s_nop 1
	v_addc_co_u32_e32 v2, vcc, v2, v3, vcc
	v_cmp_gt_u32_e32 vcc, v104, v132
	s_nop 1
	v_cndmask_b32_e64 v3, 0, 1, vcc
	v_cmp_gt_u32_e32 vcc, v107, v132
	s_nop 1
	v_addc_co_u32_e32 v2, vcc, v2, v3, vcc
	v_cmp_gt_u32_e32 vcc, v106, v132
	s_nop 1
	v_cndmask_b32_e64 v3, 0, 1, vcc
	v_cmp_gt_u32_e32 vcc, v109, v132
	s_nop 1
	v_addc_co_u32_e32 v2, vcc, v2, v3, vcc
	v_cmp_gt_u32_e32 vcc, v108, v132
	s_nop 1
	v_cndmask_b32_e64 v3, 0, 1, vcc
	v_cmp_gt_u32_e32 vcc, v111, v132
	s_nop 1
	v_addc_co_u32_e32 v2, vcc, v2, v3, vcc
	v_cmp_gt_u32_e32 vcc, v110, v132
	s_nop 1
	v_cndmask_b32_e64 v3, 0, 1, vcc
	v_cmp_gt_u32_e32 vcc, v113, v132
	s_nop 1
	v_addc_co_u32_e32 v2, vcc, v2, v3, vcc
	v_cmp_gt_u32_e32 vcc, v112, v132
	s_nop 1
	v_cndmask_b32_e64 v3, 0, 1, vcc
	v_cmp_gt_u32_e32 vcc, v115, v132
	s_nop 1
	v_addc_co_u32_e32 v2, vcc, v2, v3, vcc
	v_cmp_gt_u32_e32 vcc, v114, v132
	s_nop 1
	v_cndmask_b32_e64 v3, 0, 1, vcc
	v_cmp_gt_u32_e32 vcc, v117, v132
	s_nop 1
	v_addc_co_u32_e32 v2, vcc, v2, v3, vcc
	v_cmp_gt_u32_e32 vcc, v116, v132
	s_nop 1
	v_cndmask_b32_e64 v3, 0, 1, vcc
	v_cmp_gt_u32_e32 vcc, v119, v132
	s_nop 1
	v_addc_co_u32_e32 v2, vcc, v2, v3, vcc
	v_cmp_gt_u32_e32 vcc, v118, v132
	s_nop 1
	v_cndmask_b32_e64 v3, 0, 1, vcc
	v_cmp_gt_u32_e32 vcc, v121, v132
	s_nop 1
	v_addc_co_u32_e32 v2, vcc, v2, v3, vcc
	v_cmp_gt_u32_e32 vcc, v120, v132
	s_nop 1
	v_cndmask_b32_e64 v3, 0, 1, vcc
	v_cmp_gt_u32_e32 vcc, v123, v132
	s_nop 1
	v_addc_co_u32_e32 v2, vcc, v2, v3, vcc
	v_cmp_gt_u32_e32 vcc, v122, v132
	s_nop 1
	v_cndmask_b32_e64 v3, 0, 1, vcc
	v_cmp_gt_u32_e32 vcc, v125, v132
	s_nop 1
	v_addc_co_u32_e32 v2, vcc, v2, v3, vcc
	v_cmp_gt_u32_e32 vcc, v124, v132
	s_nop 1
	v_cndmask_b32_e64 v3, 0, 1, vcc
	v_cmp_gt_u32_e32 vcc, v126, v132
	s_nop 1
	v_addc_co_u32_e32 v2, vcc, v2, v3, vcc
	s_nop 1
	v_add_u32_dpp v2, v2, v2 quad_perm:[1,0,3,2] row_mask:0xf bank_mask:0xf bound_ctrl:1
	s_nop 1
	v_add_u32_dpp v2, v2, v2 quad_perm:[2,3,0,1] row_mask:0xf bank_mask:0xf bound_ctrl:1
	s_nop 1
	v_add_u32_dpp v2, v2, v2 row_half_mirror row_mask:0xf bank_mask:0xf bound_ctrl:1
	s_nop 1
	v_add_u32_dpp v2, v2, v2 row_mirror row_mask:0xf bank_mask:0xf bound_ctrl:1
	s_nop 1
	v_add_u32_dpp v2, v2, v2 row_bcast:15 row_mask:0xa bank_mask:0xf
	s_nop 1
	v_add_u32_dpp v2, v2, v2 row_bcast:31 row_mask:0xc bank_mask:0xf
	s_nop 0
	v_readlane_b32 s0, v2, 63
	s_sub_i32 s9, 0x100, s0
	v_mov_b64_e32 v[2:3], 0
	s_branch .LBB0_1433
